# mixers: per-CU ticket so each CU runs one RWKV scan block + one attention block (split work counters), flash loop vmcnt drain removed
# speedup vs baseline: 1.0341x; 1.0341x over previous
.LBB0_468:
	v_writelane_b32 v255, s82, 20
	s_nop 1
	v_writelane_b32 v255, s83, 21
	s_or_b64 exec, exec, s[6:7]
	s_lshl_b32 s66, s18, 9
	v_readlane_b32 s0, v255, 11
	s_or_b32 s8, s66, s0
	s_lshl_b64 s[0:1], s[8:9], 2
	v_readlane_b32 s2, v253, 20
	s_add_u32 s0, s2, s0
	v_writelane_b32 v252, s0, 57
	v_readlane_b32 s0, v253, 21
	s_addc_u32 s0, s0, s1
	s_mul_i32 s8, s18, 0x1498000
	v_writelane_b32 v253, s0, 3
	v_readlane_b32 s0, v252, 55
	v_readlane_b32 s1, v252, 56
	s_and_b64 s[0:1], s[0:1], exec
	s_movk_i32 s0, 0x220
	s_cselect_b32 s39, s0, 0x250
	s_lshl_b32 s0, s18, 3
	v_writelane_b32 v253, s0, 8
	s_lshl_b32 s0, s18, 10
	v_writelane_b32 v252, s0, 15
	s_mov_b32 s53, s9
	s_waitcnt lgkmcnt(0)
	v_writelane_b32 v252, s1, 16
	s_lshl_b64 s[0:1], s[8:9], 1
	s_add_u32 s0, s62, s0
	s_addc_u32 s1, s63, s1
	s_add_u32 s86, s0, 0x12f0000
	s_addc_u32 s87, s1, 0
	s_add_u32 s62, s0, 0x1310000
	v_writelane_b32 v255, s0, 22
	s_addc_u32 s63, s1, 0
	v_readlane_b32 s12, v252, 7
	v_writelane_b32 v255, s1, 23
	s_lshl_b64 s[0:1], s[52:53], 2
	s_barrier
	s_getreg_b32 s76, hwreg(HW_REG_XCC_ID, 0, 4)
	v_readlane_b32 s13, v252, 8
	s_add_u32 s84, s12, s0
	v_readlane_b32 s14, v252, 9
	v_readlane_b32 s15, v252, 10
	s_addc_u32 s85, s13, s1
	s_mov_b32 s67, 0
	v_writelane_b32 v252, s76, 60
	v_cmp_eq_u32_e32 vcc, 0, v234
	s_mov_b32 s99, 0
	s_and_saveexec_b64 s[100:101], vcc
	s_cbranch_execz .Lpref_done
	s_getreg_b32 s99, hwreg(HW_REG_HW_ID, 8, 7)
	s_getreg_b32 s98, hwreg(HW_REG_XCC_ID, 0, 3)
	s_lshl_b32 s98, s98, 7
	s_or_b32 s99, s99, s98
	s_lshl_b32 s99, s99, 2
	s_add_u32 s99, s99, 0x14000
	v_readlane_b32 s0, v253, 20
	v_readlane_b32 s1, v253, 21
	v_mov_b32_e32 v1, s99
	v_mov_b32_e32 v2, 1
	s_nop 4
	global_atomic_add v1, v1, v2, s[0:1] sc0
	s_waitcnt vmcnt(0)
	v_readfirstlane_b32 s99, v1
	s_nop 3
	s_and_b32 s99, s99, 1
.Lpref_done:
	s_or_b64 exec, exec, s[100:101]
	s_branch .LBB0_470

.LBB0_474:
	v_mov_b32_e32 v1, v234
	s_nop 0
	v_cmp_eq_u32_e32 vcc, 0, v1
	s_and_saveexec_b64 s[6:7], vcc
	s_cbranch_execz .LBB0_478
	v_mov_b32_e32 v2, 1
	s_cmp_eq_u32 s99, 0
	s_cbranch_scc0 .Lfetch_np
	global_atomic_add v1, v0, v2, s[96:97] sc0
	s_waitcnt vmcnt(0)
	v_readfirstlane_b32 s1, v1
	s_nop 3
	s_cmp_lt_u32 s1, 32
	s_cbranch_scc1 .Lfetch_store
	global_atomic_add v1, v0, v2, s[96:97] offset:4 sc0
	s_waitcnt vmcnt(0)
	v_readfirstlane_b32 s1, v1
	s_nop 3
	s_add_i32 s1, s1, 32
	s_branch .Lfetch_store
.Lfetch_np:
	global_atomic_add v1, v0, v2, s[96:97] offset:4 sc0
	s_waitcnt vmcnt(0)
	v_readfirstlane_b32 s1, v1
	s_nop 3
	s_add_i32 s1, s1, 32
	s_cmp_lt_i32 s1, s39
	s_cbranch_scc1 .Lfetch_store
	global_atomic_add v1, v0, v2, s[96:97] sc0
	s_waitcnt vmcnt(0)
	v_readfirstlane_b32 s1, v1
	s_nop 3
	s_cmp_lt_u32 s1, 32
	s_cbranch_scc1 .Lfetch_store
	s_mov_b32 s1, s39
.Lfetch_store:
	v_mov_b32_e32 v1, s1
	v_mov_b32_e32 v2, s21
	ds_write_b32 v2, v1

.LBB0_510:
	s_lshl_b32 s72, s70, 14
	s_add_i32 s72, s72, 0
	v_add_u32_e32 v1, s72, v90
	v_add_u32_e32 v2, s72, v91
	ds_read_b128 v[28:31], v1
	ds_read_b128 v[32:35], v1 offset:2048
	ds_read_b128 v[36:39], v2
	ds_read_b128 v[40:43], v2 offset:2048
	ds_read_b128 v[44:47], v1 offset:4096
	ds_read_b128 v[48:51], v1 offset:6144
	ds_read_b128 v[52:55], v2 offset:4096
	ds_read_b128 v[56:59], v2 offset:6144
	s_waitcnt lgkmcnt(0)
	v_mfma_f32_16x16x32_bf16 v[28:31], v[28:31], v[4:7], 0
	v_add_u32_e32 v1, s72, v92
	v_add_u32_e32 v2, s72, v93
	v_mfma_f32_16x16x32_bf16 v[74:77], v[36:39], v[8:11], v[28:31]
	v_mfma_f32_16x16x32_bf16 v[28:31], v[32:35], v[4:7], 0
	v_mfma_f32_16x16x32_bf16 v[68:71], v[40:43], v[8:11], v[28:31]
	v_mfma_f32_16x16x32_bf16 v[28:31], v[44:47], v[4:7], 0
	v_mfma_f32_16x16x32_bf16 v[64:67], v[52:55], v[8:11], v[28:31]
	v_mfma_f32_16x16x32_bf16 v[28:31], v[48:51], v[4:7], 0
	v_mfma_f32_16x16x32_bf16 v[60:63], v[56:59], v[8:11], v[28:31]
	ds_read2st64_b64 v[56:59], v1 offset0:16 offset1:20
	ds_read2st64_b64 v[52:55], v2 offset0:16 offset1:20
	ds_read2st64_b64 v[48:51], v1 offset0:24 offset1:28
	ds_read2st64_b64 v[44:47], v2 offset0:24 offset1:28
	v_add_u32_e32 v1, s72, v96
	v_add_u32_e32 v2, s72, v97
	ds_read2st64_b64 v[40:43], v1 offset0:16 offset1:20
	ds_read2st64_b64 v[36:39], v2 offset0:16 offset1:20
	ds_read2st64_b64 v[32:35], v1 offset0:24 offset1:28
	ds_read2st64_b64 v[28:31], v2 offset0:24 offset1:28
	s_cmp_gt_u32 s71, 7
	s_mov_b32 s71, 0x3e38aa3b
	s_cbranch_scc1 .LBB0_544
	v_mov_b32_e32 v73, 0xff800000
	v_add_u32_e32 v1, s69, v98
	v_mov_b32_e32 v72, 0xff800000
	s_and_saveexec_b64 vcc, s[40:41]
	s_cbranch_execz .LBB0_513
	v_add_u32_e32 v2, 0x103a0, v1
	ds_read_b32 v3, v2
	v_mov_b32_e32 v2, v74
	s_waitcnt lgkmcnt(0)
	v_pk_mul_f32 v[2:3], v[2:3], s[4:5]
	s_nop 0
	v_add_f32_e32 v72, v2, v3

.LBB0_567:
	s_lshl_b32 s14, s28, 14
	s_add_i32 s14, s14, 0
	v_add_u32_e32 v1, s14, v129
	v_add_u32_e32 v2, s14, v130
	ds_read_b128 v[52:55], v1
	ds_read_b128 v[56:59], v1 offset:2048
	ds_read_b128 v[60:63], v2
	ds_read_b128 v[64:67], v2 offset:2048
	ds_read_b128 v[68:71], v1 offset:4096
	ds_read_b128 v[72:75], v1 offset:6144
	ds_read_b128 v[76:79], v2 offset:4096
	ds_read_b128 v[80:83], v2 offset:6144
	s_waitcnt lgkmcnt(0)
	v_mfma_f32_16x16x32_bf16 v[84:87], v[52:55], v[4:7], 0
	v_add_u32_e32 v1, s14, v131
	v_add_u32_e32 v2, s14, v132
	ds_read2st64_b64 v[88:91], v1 offset0:16 offset1:20
	v_mfma_f32_16x16x32_bf16 v[52:55], v[52:55], v[12:15], 0
	v_mfma_f32_16x16x32_bf16 v[96:99], v[60:63], v[16:19], v[52:55]
	v_mfma_f32_16x16x32_bf16 v[52:55], v[56:59], v[4:7], 0
	v_mfma_f32_16x16x32_bf16 v[56:59], v[56:59], v[12:15], 0
	v_mfma_f32_16x16x32_bf16 v[108:111], v[64:67], v[8:11], v[52:55]
	v_mfma_f32_16x16x32_bf16 v[92:95], v[64:67], v[16:19], v[56:59]
	v_mfma_f32_16x16x32_bf16 v[52:55], v[68:71], v[4:7], 0
	v_mfma_f32_16x16x32_bf16 v[56:59], v[68:71], v[12:15], 0
	v_mfma_f32_16x16x32_bf16 v[104:107], v[76:79], v[8:11], v[52:55]
	v_mfma_f32_16x16x32_bf16 v[68:71], v[76:79], v[16:19], v[56:59]
	v_mfma_f32_16x16x32_bf16 v[52:55], v[72:75], v[4:7], 0
	v_mfma_f32_16x16x32_bf16 v[56:59], v[72:75], v[12:15], 0
	v_mfma_f32_16x16x32_bf16 v[112:115], v[60:63], v[8:11], v[84:87]
	v_mfma_f32_16x16x32_bf16 v[100:103], v[80:83], v[8:11], v[52:55]
	v_mfma_f32_16x16x32_bf16 v[56:59], v[80:83], v[16:19], v[56:59]
	s_nop 0
	ds_read2st64_b64 v[84:87], v2 offset0:16 offset1:20
	ds_read2st64_b64 v[80:83], v1 offset0:24 offset1:28
	ds_read2st64_b64 v[76:79], v2 offset0:24 offset1:28
	v_add_u32_e32 v1, s14, v133
	v_add_u32_e32 v2, s14, v134
	ds_read2st64_b64 v[72:75], v1 offset0:16 offset1:20
	ds_read2st64_b64 v[64:67], v2 offset0:16 offset1:20
	ds_read2st64_b64 v[60:63], v1 offset0:24 offset1:28
	ds_read2st64_b64 v[52:55], v2 offset0:24 offset1:28
	v_max_f32_e32 v1, v113, v113
	v_max_f32_e32 v2, v112, v112
	v_max_f32_e32 v1, v2, v1
	v_max_f32_e32 v2, v115, v115
	v_max_f32_e32 v3, v114, v114
	v_max_f32_e32 v2, v3, v2
	v_max_f32_e32 v3, v111, v111
	v_max_f32_e32 v138, v110, v110
	v_max_f32_e32 v3, v138, v3
	v_max3_f32 v3, v108, v109, v3
	v_max3_f32 v1, v1, v2, v3
	v_max_f32_e32 v2, v107, v107
	v_max_f32_e32 v3, v106, v106
	v_max_f32_e32 v2, v3, v2
	v_max_f32_e32 v3, v103, v103
	v_max_f32_e32 v138, v102, v102
	v_max_f32_e32 v3, v138, v3
	v_max3_f32 v2, v104, v105, v2
	v_max3_f32 v3, v100, v101, v3
	v_max3_f32 v1, v1, v2, v3
	v_mov_b32_e32 v2, v1
	s_nop 1
	v_permlane16_swap_b32_e32 v1, v2
	v_max_f32_e32 v2, v2, v2
	v_max_f32_e32 v1, v1, v1
	v_max_f32_e32 v1, v1, v2
	v_mov_b32_e32 v2, v1
	s_nop 1
	v_permlane32_swap_b32_e32 v1, v2
	v_max_f32_e32 v2, v2, v2
	v_max_f32_e32 v1, v1, v1
	v_max_f32_e32 v1, v1, v2
	v_mul_f32_e32 v1, 0x3e38aa3b, v1
	v_max_f32_e32 v2, v137, v137
	v_max_f32_e32 v1, v2, v1
	v_cmp_gt_f32_e32 vcc, v1, v137
	s_cbranch_vccz .LBB0_569
	v_sub_f32_e32 v2, v137, v1
	v_exp_f32_e32 v2, v2
	s_nop 0
	v_mul_f32_e32 v135, v135, v2
	v_pk_mul_f32 v[50:51], v[50:51], v[2:3] op_sel_hi:[1,0]
	v_pk_mul_f32 v[48:49], v[48:49], v[2:3] op_sel_hi:[1,0]
	v_pk_mul_f32 v[46:47], v[46:47], v[2:3] op_sel_hi:[1,0]
	v_pk_mul_f32 v[44:45], v[44:45], v[2:3] op_sel_hi:[1,0]
	v_pk_mul_f32 v[42:43], v[42:43], v[2:3] op_sel_hi:[1,0]
	v_pk_mul_f32 v[40:41], v[40:41], v[2:3] op_sel_hi:[1,0]
	v_pk_mul_f32 v[38:39], v[38:39], v[2:3] op_sel_hi:[1,0]
	v_pk_mul_f32 v[36:37], v[36:37], v[2:3] op_sel_hi:[1,0]

	.amdhsa_kernel _Z14fwd_megakernel6Params
		.amdhsa_group_segment_fixed_size 0
		.amdhsa_private_segment_fixed_size 0
		.amdhsa_kernarg_size 528
		.amdhsa_user_sgpr_count 2
		.amdhsa_user_sgpr_dispatch_ptr 0
		.amdhsa_user_sgpr_queue_ptr 0
		.amdhsa_user_sgpr_kernarg_segment_ptr 1
		.amdhsa_user_sgpr_dispatch_id 0
		.amdhsa_user_sgpr_kernarg_preload_length 0
		.amdhsa_user_sgpr_kernarg_preload_offset 0
		.amdhsa_user_sgpr_private_segment_size 0
		.amdhsa_uses_dynamic_stack 0
		.amdhsa_enable_private_segment 0
		.amdhsa_system_sgpr_workgroup_id_x 1
		.amdhsa_system_sgpr_workgroup_id_y 0
		.amdhsa_system_sgpr_workgroup_id_z 0
		.amdhsa_system_sgpr_workgroup_info 0
		.amdhsa_system_vgpr_workitem_id 2
		.amdhsa_next_free_vgpr 256
		.amdhsa_next_free_sgpr 102
		.amdhsa_accum_offset 256
		.amdhsa_reserve_vcc 1
		.amdhsa_float_round_mode_32 0
		.amdhsa_float_round_mode_16_64 0
		.amdhsa_float_denorm_mode_32 3
		.amdhsa_float_denorm_mode_16_64 3
		.amdhsa_dx10_clamp 1
		.amdhsa_ieee_mode 1
		.amdhsa_fp16_overflow 0
		.amdhsa_tg_split 0
		.amdhsa_exception_fp_ieee_invalid_op 0
		.amdhsa_exception_fp_denorm_src 0
		.amdhsa_exception_fp_ieee_div_zero 0
		.amdhsa_exception_fp_ieee_overflow 0
		.amdhsa_exception_fp_ieee_underflow 0
		.amdhsa_exception_fp_ieee_inexact 0
		.amdhsa_exception_int_div_zero 0
	.end_amdhsa_kernel

amdhsa.kernels:
  - .agpr_count:     0
    .args:
      - .offset:         0
        .size:           272
        .value_kind:     by_value
      - .offset:         272
        .size:           4
        .value_kind:     hidden_block_count_x
      - .offset:         276
        .size:           4
        .value_kind:     hidden_block_count_y
      - .offset:         280
        .size:           4
        .value_kind:     hidden_block_count_z
      - .offset:         284
        .size:           2
        .value_kind:     hidden_group_size_x
      - .offset:         286
        .size:           2
        .value_kind:     hidden_group_size_y
      - .offset:         288
        .size:           2
        .value_kind:     hidden_group_size_z
      - .offset:         290
        .size:           2
        .value_kind:     hidden_remainder_x
      - .offset:         292
        .size:           2
        .value_kind:     hidden_remainder_y
      - .offset:         294
        .size:           2
        .value_kind:     hidden_remainder_z
      - .offset:         312
        .size:           8
        .value_kind:     hidden_global_offset_x
      - .offset:         320
        .size:           8
        .value_kind:     hidden_global_offset_y
      - .offset:         328
        .size:           8
        .value_kind:     hidden_global_offset_z
      - .offset:         336
        .size:           2
        .value_kind:     hidden_grid_dims
      - .offset:         360
        .size:           8
        .value_kind:     hidden_multigrid_sync_arg
      - .offset:         392
        .size:           4
        .value_kind:     hidden_dynamic_lds_size
    .group_segment_fixed_size: 0
    .kernarg_segment_align: 8
    .kernarg_segment_size: 528
    .language:       OpenCL C
    .language_version:
      - 2
      - 0
    .max_flat_workgroup_size: 256
    .name:           _Z14fwd_megakernel6Params
    .private_segment_fixed_size: 0
    .sgpr_count:     108
    .sgpr_spill_count: 262
    .symbol:         _Z14fwd_megakernel6Params.kd
    .uniform_work_group_size: 1
    .uses_dynamic_stack: false
    .vgpr_count:     256
    .vgpr_spill_count: 0
    .wavefront_size: 64
